# softmax row max as two interleaved v_max3 chains (no canonicalizing v_max, no add of zero), fused with the lazy rescale test and permlane exchange; on top of QK1 read hoist and unrolled scan
# speedup vs baseline: 1.0280x; 1.0018x over previous
; template <int NS, int SI>
; __device__ __forceinline__ void attn_stream(const unsigned char* kbase, const unsigned char* vbase, const unsigned char* q_rd, bool mask_tail, int last_valid, int hh, float sc,
;                                             f32x16 (&O)[4], float& mrun, float& lrun) {
;     ...
;     float mx = __builtin_amdgcn_fmed3f(S0[0], S1[0], __builtin_inff());
; #pragma unroll
;     for (int r = 1; r < 16; ++r) { mx = __builtin_amdgcn_fmed3f(mx, S0[r], __builtin_inff()); mx = __builtin_amdgcn_fmed3f(mx, S1[r], __builtin_inff()); }
;     mx = fmaxf(mx, __shfl_xor(mx, 32));
;     const float mn = fmaxf(mrun, mx * sc);
;     const float alpha = __builtin_amdgcn_exp2f(mrun - mn);
;     mrun = mn;
;     f32x2 ls2 = {0.f, 0.f};
;     const f32x2 sc2 = {sc, sc}, mn2 = {mn, mn};
; #pragma unroll
;     for (int r = 0; r < 16; r += 2) {
;         const f32x2 t0 = (f32x2){S0[r], S0[r + 1]} * sc2 - mn2, t1 = (f32x2){S1[r], S1[r + 1]} * sc2 - mn2;
;         const f32x2 p0 = {__builtin_amdgcn_exp2f(t0.x), __builtin_amdgcn_exp2f(t0.y)}, p1 = {__builtin_amdgcn_exp2f(t1.x), __builtin_amdgcn_exp2f(t1.y)};
;         S0[r] = p0.x; S0[r + 1] = p0.y; S1[r] = p1.x; S1[r + 1] = p1.y; ls2 += p0 + p1;
;     }
;     lrun = lrun * alpha + (ls2.x + ls2.y);
;     if (__any(alpha != 1.0f)) {
; #pragma unroll
;         for (int d = 0; d < 4; ++d) O[d] = O[d] * alpha;
.LBB0_1165:
	s_nop 9
	v_max3_f32 v200, v128, v129, v130
	v_max3_f32 v202, v144, v145, v146
	v_max3_f32 v200, v200, v131, v132
	v_max3_f32 v202, v202, v147, v148
	v_max3_f32 v200, v200, v133, v134
	v_max3_f32 v202, v202, v149, v150
	v_max3_f32 v200, v200, v135, v136
	v_max3_f32 v202, v202, v151, v152
	v_max3_f32 v200, v200, v137, v138
	v_max3_f32 v202, v202, v153, v154
	v_max3_f32 v200, v200, v139, v140
	v_max3_f32 v202, v202, v155, v156
	v_max3_f32 v200, v200, v141, v142
	v_max3_f32 v202, v202, v157, v158
	v_max3_f32 v200, v200, v143, v159
	v_max_f32_e32 v200, v200, v202
	v_mov_b32_e32 v202, v200
	s_nop 1
	v_permlane32_swap_b32_e32 v202, v200
	v_max_f32_e32 v200, v200, v202
	v_mul_f32_e32 v200, 0x3e38aa3b, v200
	v_max_f32_e32 v200, v228, v200
	v_sub_f32_e32 v202, v200, v228
	v_cmp_lt_f32_e32 vcc, 4.0, v202
	s_nop 1
	v_cndmask_b32_e32 v200, v228, v200, vcc
	v_sub_f32_e32 v202, v228, v200
	v_exp_f32_e32 v202, v202
	s_nop 0
	v_cmp_neq_f32_e32 vcc, 1.0, v202
	s_cbranch_vccz .LBB0_1167
	v_pk_mul_f32 v[78:79], v[78:79], v[202:203] op_sel_hi:[1,0]
	v_pk_mul_f32 v[76:77], v[76:77], v[202:203] op_sel_hi:[1,0]
	v_pk_mul_f32 v[74:75], v[74:75], v[202:203] op_sel_hi:[1,0]
	v_pk_mul_f32 v[72:73], v[72:73], v[202:203] op_sel_hi:[1,0]
	v_pk_mul_f32 v[70:71], v[70:71], v[202:203] op_sel_hi:[1,0]
	v_pk_mul_f32 v[68:69], v[68:69], v[202:203] op_sel_hi:[1,0]
	v_pk_mul_f32 v[66:67], v[66:67], v[202:203] op_sel_hi:[1,0]
	v_pk_mul_f32 v[64:65], v[64:65], v[202:203] op_sel_hi:[1,0]
	v_pk_mul_f32 v[62:63], v[62:63], v[202:203] op_sel_hi:[1,0]
	v_pk_mul_f32 v[60:61], v[60:61], v[202:203] op_sel_hi:[1,0]
	v_pk_mul_f32 v[58:59], v[58:59], v[202:203] op_sel_hi:[1,0]
	v_pk_mul_f32 v[56:57], v[56:57], v[202:203] op_sel_hi:[1,0]
	v_pk_mul_f32 v[54:55], v[54:55], v[202:203] op_sel_hi:[1,0]
	v_pk_mul_f32 v[52:53], v[52:53], v[202:203] op_sel_hi:[1,0]
	v_pk_mul_f32 v[50:51], v[50:51], v[202:203] op_sel_hi:[1,0]
	v_pk_mul_f32 v[48:49], v[48:49], v[202:203] op_sel_hi:[1,0]
	v_pk_mul_f32 v[46:47], v[46:47], v[202:203] op_sel_hi:[1,0]
	v_pk_mul_f32 v[44:45], v[44:45], v[202:203] op_sel_hi:[1,0]
	v_pk_mul_f32 v[42:43], v[42:43], v[202:203] op_sel_hi:[1,0]
	v_pk_mul_f32 v[40:41], v[40:41], v[202:203] op_sel_hi:[1,0]
	v_pk_mul_f32 v[38:39], v[38:39], v[202:203] op_sel_hi:[1,0]
	v_pk_mul_f32 v[36:37], v[36:37], v[202:203] op_sel_hi:[1,0]
	v_pk_mul_f32 v[34:35], v[34:35], v[202:203] op_sel_hi:[1,0]
	v_pk_mul_f32 v[32:33], v[32:33], v[202:203] op_sel_hi:[1,0]
	v_pk_mul_f32 v[14:15], v[14:15], v[202:203] op_sel_hi:[1,0]
	v_pk_mul_f32 v[12:13], v[12:13], v[202:203] op_sel_hi:[1,0]
	v_pk_mul_f32 v[10:11], v[10:11], v[202:203] op_sel_hi:[1,0]
	v_pk_mul_f32 v[8:9], v[8:9], v[202:203] op_sel_hi:[1,0]
	v_pk_mul_f32 v[6:7], v[6:7], v[202:203] op_sel_hi:[1,0]
	v_pk_mul_f32 v[4:5], v[4:5], v[202:203] op_sel_hi:[1,0]
	v_pk_mul_f32 v[2:3], v[2:3], v[202:203] op_sel_hi:[1,0]
	v_pk_mul_f32 v[0:1], v[0:1], v[202:203] op_sel_hi:[1,0]
.LBB0_1167:
	v_pk_fma_f32 v[128:129], v[128:129], s[58:59], v[200:201] op_sel_hi:[1,0,0] neg_lo:[0,0,1] neg_hi:[0,0,1]
	v_pk_fma_f32 v[144:145], v[144:145], s[58:59], v[200:201] op_sel_hi:[1,0,0] neg_lo:[0,0,1] neg_hi:[0,0,1]
	v_exp_f32_e32 v232, v128
	v_exp_f32_e32 v233, v129
	v_exp_f32_e32 v144, v144
	v_exp_f32_e32 v145, v145
	v_pk_fma_f32 v[128:129], v[130:131], s[58:59], v[200:201] op_sel_hi:[1,0,0] neg_lo:[0,0,1] neg_hi:[0,0,1]
	v_pk_fma_f32 v[130:131], v[146:147], s[58:59], v[200:201] op_sel_hi:[1,0,0] neg_lo:[0,0,1] neg_hi:[0,0,1]
	v_exp_f32_e32 v146, v128
	v_exp_f32_e32 v147, v129
	v_exp_f32_e32 v234, v130
	v_exp_f32_e32 v235, v131
	v_pk_fma_f32 v[132:133], v[132:133], s[58:59], v[200:201] op_sel_hi:[1,0,0] neg_lo:[0,0,1] neg_hi:[0,0,1]
	v_pk_fma_f32 v[148:149], v[148:149], s[58:59], v[200:201] op_sel_hi:[1,0,0] neg_lo:[0,0,1] neg_hi:[0,0,1]
	v_exp_f32_e32 v236, v132
	v_exp_f32_e32 v237, v133
	v_exp_f32_e32 v148, v148
	v_exp_f32_e32 v149, v149
	v_pk_fma_f32 v[132:133], v[134:135], s[58:59], v[200:201] op_sel_hi:[1,0,0] neg_lo:[0,0,1] neg_hi:[0,0,1]
	v_pk_fma_f32 v[134:135], v[150:151], s[58:59], v[200:201] op_sel_hi:[1,0,0] neg_lo:[0,0,1] neg_hi:[0,0,1]
	v_exp_f32_e32 v150, v132
	v_exp_f32_e32 v151, v133
	v_exp_f32_e32 v238, v134
	v_exp_f32_e32 v239, v135
	v_pk_fma_f32 v[132:133], v[136:137], s[58:59], v[200:201] op_sel_hi:[1,0,0] neg_lo:[0,0,1] neg_hi:[0,0,1]
	v_pk_fma_f32 v[134:135], v[152:153], s[58:59], v[200:201] op_sel_hi:[1,0,0] neg_lo:[0,0,1] neg_hi:[0,0,1]
	v_pk_add_f32 v[128:129], v[144:145], v[232:233]
	v_exp_f32_e32 v152, v132
	v_exp_f32_e32 v153, v133
	v_exp_f32_e32 v240, v134
	v_exp_f32_e32 v241, v135
	v_pk_fma_f32 v[132:133], v[138:139], s[58:59], v[200:201] op_sel_hi:[1,0,0] neg_lo:[0,0,1] neg_hi:[0,0,1]
	v_pk_fma_f32 v[134:135], v[154:155], s[58:59], v[200:201] op_sel_hi:[1,0,0] neg_lo:[0,0,1] neg_hi:[0,0,1]
	v_pk_add_f32 v[130:131], v[234:235], v[146:147]
	v_exp_f32_e32 v154, v132
	v_exp_f32_e32 v155, v133
	v_exp_f32_e32 v242, v134
	v_exp_f32_e32 v243, v135
	v_pk_fma_f32 v[132:133], v[140:141], s[58:59], v[200:201] op_sel_hi:[1,0,0] neg_lo:[0,0,1] neg_hi:[0,0,1]
	v_pk_fma_f32 v[134:135], v[156:157], s[58:59], v[200:201] op_sel_hi:[1,0,0] neg_lo:[0,0,1] neg_hi:[0,0,1]
	v_pk_add_f32 v[128:129], v[130:131], v[128:129]
	v_pk_add_f32 v[130:131], v[148:149], v[236:237]
	v_exp_f32_e32 v140, v132
	v_exp_f32_e32 v141, v133
	v_exp_f32_e32 v156, v134
	v_exp_f32_e32 v157, v135
	v_pk_fma_f32 v[132:133], v[142:143], s[58:59], v[200:201] op_sel_hi:[1,0,0] neg_lo:[0,0,1] neg_hi:[0,0,1]
	v_pk_fma_f32 v[134:135], v[158:159], s[58:59], v[200:201] op_sel_hi:[1,0,0] neg_lo:[0,0,1] neg_hi:[0,0,1]
	v_pk_add_f32 v[128:129], v[130:131], v[128:129]
	v_pk_add_f32 v[130:131], v[238:239], v[150:151]
	v_exp_f32_e32 v142, v132
	v_exp_f32_e32 v143, v133
	v_exp_f32_e32 v158, v134
	v_exp_f32_e32 v159, v135
	v_pk_add_f32 v[128:129], v[130:131], v[128:129]
	v_pk_add_f32 v[130:131], v[240:241], v[152:153]
	s_nop 0
	v_pk_add_f32 v[128:129], v[130:131], v[128:129]
	v_pk_add_f32 v[130:131], v[242:243], v[154:155]
	s_nop 0
	v_pk_add_f32 v[128:129], v[130:131], v[128:129]
	v_pk_add_f32 v[130:131], v[156:157], v[140:141]
	s_nop 0
	v_pk_add_f32 v[128:129], v[130:131], v[128:129]
	v_pk_add_f32 v[130:131], v[158:159], v[142:143]
	s_nop 0
	v_pk_add_f32 v[128:129], v[130:131], v[128:129]
	s_nop 0
	v_add_f32_e32 v231, v128, v129
	v_fmac_f32_e32 v231, v226, v202
	ds_read_b64_tr_b16 v[128:129], v225 offset:17408
	ds_read_b64_tr_b16 v[130:131], v225 offset:19968
	ds_read_b64_tr_b16 v[138:139], v225 offset:20032
	ds_read_b64_tr_b16 v[136:137], v225 offset:17472
	v_cvt_pk_bf16_f32 v132, v232, v233
	v_cvt_pk_bf16_f32 v133, v146, v147
	v_cvt_pk_bf16_f32 v134, v236, v237
	v_cvt_pk_bf16_f32 v135, v150, v151
	s_waitcnt lgkmcnt(2)
; template <int NS, int SI>
; __device__ __forceinline__ void attn_stream(const unsigned char* kbase, const unsigned char* vbase, const unsigned char* q_rd, bool mask_tail, int last_valid, int hh, float sc,
;                                             f32x16 (&O)[4], float& mrun, float& lrun) {
;     ...
;     __builtin_amdgcn_sched_barrier(0);
;     PV_GROUP(S0, 0, 0) PV_GROUP(S0, 0, 1) PV_GROUP(S1, 1, 0) PV_GROUP(S1, 1, 1)
	s_nop 0
	v_mfma_f32_32x32x16_bf16 v[64:79], v[128:131], v[132:135], v[64:79]
	s_waitcnt lgkmcnt(0)
	v_mfma_f32_32x32x16_bf16 v[48:63], v[136:139], v[132:135], v[48:63]
	ds_read_b64_tr_b16 v[128:129], v225 offset:17536
	ds_read_b64_tr_b16 v[130:131], v225 offset:20096
	ds_read_b64_tr_b16 v[138:139], v225 offset:20160
	ds_read_b64_tr_b16 v[136:137], v225 offset:17600
	s_waitcnt lgkmcnt(2)
	v_mfma_f32_32x32x16_bf16 v[32:47], v[128:131], v[132:135], v[32:47]
	s_waitcnt lgkmcnt(0)
	v_mfma_f32_32x32x16_bf16 v[0:15], v[136:139], v[132:135], v[0:15]
	ds_read_b64_tr_b16 v[128:129], v225 offset:22528
	ds_read_b64_tr_b16 v[130:131], v225 offset:25088
	ds_read_b64_tr_b16 v[138:139], v225 offset:25152
	ds_read_b64_tr_b16 v[136:137], v225 offset:22592
	v_cvt_pk_bf16_f32 v132, v152, v153
	v_cvt_pk_bf16_f32 v133, v154, v155
	v_cvt_pk_bf16_f32 v134, v140, v141
	v_cvt_pk_bf16_f32 v135, v142, v143
	s_waitcnt lgkmcnt(2)
	s_nop 0
	v_mfma_f32_32x32x16_bf16 v[64:79], v[128:131], v[132:135], v[64:79]
	s_waitcnt lgkmcnt(0)
	v_mfma_f32_32x32x16_bf16 v[48:63], v[136:139], v[132:135], v[48:63]
	ds_read_b64_tr_b16 v[128:129], v225 offset:22656
	ds_read_b64_tr_b16 v[130:131], v225 offset:25216
	ds_read_b64_tr_b16 v[138:139], v225 offset:25280
	ds_read_b64_tr_b16 v[136:137], v225 offset:22720
	s_waitcnt lgkmcnt(2)
	v_mfma_f32_32x32x16_bf16 v[32:47], v[128:131], v[132:135], v[32:47]
	s_waitcnt lgkmcnt(0)
	v_mfma_f32_32x32x16_bf16 v[0:15], v[136:139], v[132:135], v[0:15]
	ds_read_b64_tr_b16 v[128:129], v225 offset:27648
	ds_read_b64_tr_b16 v[130:131], v225 offset:30208
	ds_read_b64_tr_b16 v[138:139], v225 offset:30272
	ds_read_b64_tr_b16 v[136:137], v225 offset:27712
	v_cvt_pk_bf16_f32 v132, v144, v145
	v_cvt_pk_bf16_f32 v133, v234, v235
	v_cvt_pk_bf16_f32 v134, v148, v149
	v_cvt_pk_bf16_f32 v135, v238, v239
	s_waitcnt lgkmcnt(2)
	s_nop 0
	v_mfma_f32_32x32x16_bf16 v[64:79], v[128:131], v[132:135], v[64:79]
	s_waitcnt lgkmcnt(0)
	v_mfma_f32_32x32x16_bf16 v[48:63], v[136:139], v[132:135], v[48:63]
	ds_read_b64_tr_b16 v[128:129], v225 offset:27776
	ds_read_b64_tr_b16 v[130:131], v225 offset:30336
	ds_read_b64_tr_b16 v[138:139], v225 offset:30400
	ds_read_b64_tr_b16 v[136:137], v225 offset:27840
	s_waitcnt lgkmcnt(2)
	v_mfma_f32_32x32x16_bf16 v[32:47], v[128:131], v[132:135], v[32:47]
	s_waitcnt lgkmcnt(0)
	v_mfma_f32_32x32x16_bf16 v[0:15], v[136:139], v[132:135], v[0:15]
	ds_read_b64_tr_b16 v[128:129], v225 offset:32768
	ds_read_b64_tr_b16 v[130:131], v225 offset:35328
	ds_read_b64_tr_b16 v[138:139], v225 offset:35392
	ds_read_b64_tr_b16 v[136:137], v225 offset:32832
	v_cvt_pk_bf16_f32 v132, v240, v241
	v_cvt_pk_bf16_f32 v133, v242, v243
	v_cvt_pk_bf16_f32 v134, v156, v157
	v_cvt_pk_bf16_f32 v135, v158, v159
	s_waitcnt lgkmcnt(2)
	s_nop 0
	v_mfma_f32_32x32x16_bf16 v[64:79], v[128:131], v[132:135], v[64:79]
	s_waitcnt lgkmcnt(0)
	v_mfma_f32_32x32x16_bf16 v[48:63], v[136:139], v[132:135], v[48:63]
	ds_read_b64_tr_b16 v[128:129], v225 offset:32896
	ds_read_b64_tr_b16 v[130:131], v225 offset:35456
	ds_read_b64_tr_b16 v[138:139], v225 offset:35520
	ds_read_b64_tr_b16 v[136:137], v225 offset:32960
	s_waitcnt lgkmcnt(2)
	v_mfma_f32_32x32x16_bf16 v[32:47], v[128:131], v[132:135], v[32:47]
	s_waitcnt lgkmcnt(0)
	v_mfma_f32_32x32x16_bf16 v[0:15], v[136:139], v[132:135], v[0:15]
	ds_read_b128 v[144:147], v222 offset:128
	ds_read_b128 v[232:235], v230 offset:160
	ds_read_b128 v[236:239], v222 offset:160
	ds_read_b128 v[148:151], v230 offset:8832
	ds_read_b128 v[240:243], v230 offset:8864
	v_mov_b32_e32 v228, v200
	v_mov_b32_e32 v226, v231

; template <int NS, int SI>
; __device__ __forceinline__ void attn_stream(const unsigned char* kbase, const unsigned char* vbase, const unsigned char* q_rd, bool mask_tail, int last_valid, int hh, float sc,
;                                             f32x16 (&O)[4], float& mrun, float& lrun) {
;     ...
;     float mx = __builtin_amdgcn_fmed3f(S0[0], S1[0], __builtin_inff());
; #pragma unroll
;     for (int r = 1; r < 16; ++r) { mx = __builtin_amdgcn_fmed3f(mx, S0[r], __builtin_inff()); mx = __builtin_amdgcn_fmed3f(mx, S1[r], __builtin_inff()); }
;     mx = fmaxf(mx, __shfl_xor(mx, 32));
;     const float mn = fmaxf(mrun, mx * sc);
;     const float alpha = __builtin_amdgcn_exp2f(mrun - mn);
;     mrun = mn;
;     f32x2 ls2 = {0.f, 0.f};
;     const f32x2 sc2 = {sc, sc}, mn2 = {mn, mn};
; #pragma unroll
;     for (int r = 0; r < 16; r += 2) {
;         const f32x2 t0 = (f32x2){S0[r], S0[r + 1]} * sc2 - mn2, t1 = (f32x2){S1[r], S1[r + 1]} * sc2 - mn2;
;         const f32x2 p0 = {__builtin_amdgcn_exp2f(t0.x), __builtin_amdgcn_exp2f(t0.y)}, p1 = {__builtin_amdgcn_exp2f(t1.x), __builtin_amdgcn_exp2f(t1.y)};
;         S0[r] = p0.x; S0[r + 1] = p0.y; S1[r] = p1.x; S1[r + 1] = p1.y; ls2 += p0 + p1;
;     }
;     lrun = lrun * alpha + (ls2.x + ls2.y);
;     if (__any(alpha != 1.0f)) {
; #pragma unroll
;         for (int d = 0; d < 4; ++d) O[d] = O[d] * alpha;
.LBB0_1177:
	s_nop 9
	v_max3_f32 v200, v128, v129, v130
	v_max3_f32 v202, v144, v145, v146
	v_max3_f32 v200, v200, v131, v132
	v_max3_f32 v202, v202, v147, v148
	v_max3_f32 v200, v200, v133, v134
	v_max3_f32 v202, v202, v149, v150
	v_max3_f32 v200, v200, v135, v136
	v_max3_f32 v202, v202, v151, v152
	v_max3_f32 v200, v200, v137, v138
	v_max3_f32 v202, v202, v153, v154
	v_max3_f32 v200, v200, v139, v140
	v_max3_f32 v202, v202, v155, v156
	v_max3_f32 v200, v200, v141, v142
	v_max3_f32 v202, v202, v157, v158
	v_max3_f32 v200, v200, v143, v159
	v_max_f32_e32 v200, v200, v202
	v_mov_b32_e32 v202, v200
	s_nop 1
	v_permlane32_swap_b32_e32 v202, v200
	v_max_f32_e32 v200, v200, v202
	v_mul_f32_e32 v200, 0x3e38aa3b, v200
	v_max_f32_e32 v200, v229, v200
	v_sub_f32_e32 v202, v200, v229
	v_cmp_lt_f32_e32 vcc, 4.0, v202
	s_nop 1
	v_cndmask_b32_e32 v200, v229, v200, vcc
	v_sub_f32_e32 v202, v229, v200
	v_exp_f32_e32 v202, v202
	s_nop 0
	v_cmp_neq_f32_e32 vcc, 1.0, v202
	s_cbranch_vccz .LBB0_1179
	v_pk_mul_f32 v[126:127], v[126:127], v[202:203] op_sel_hi:[1,0]
	v_pk_mul_f32 v[124:125], v[124:125], v[202:203] op_sel_hi:[1,0]
	v_pk_mul_f32 v[122:123], v[122:123], v[202:203] op_sel_hi:[1,0]
	v_pk_mul_f32 v[120:121], v[120:121], v[202:203] op_sel_hi:[1,0]
	v_pk_mul_f32 v[118:119], v[118:119], v[202:203] op_sel_hi:[1,0]
	v_pk_mul_f32 v[116:117], v[116:117], v[202:203] op_sel_hi:[1,0]
	v_pk_mul_f32 v[114:115], v[114:115], v[202:203] op_sel_hi:[1,0]
	v_pk_mul_f32 v[112:113], v[112:113], v[202:203] op_sel_hi:[1,0]
	v_pk_mul_f32 v[110:111], v[110:111], v[202:203] op_sel_hi:[1,0]
	v_pk_mul_f32 v[108:109], v[108:109], v[202:203] op_sel_hi:[1,0]
	v_pk_mul_f32 v[106:107], v[106:107], v[202:203] op_sel_hi:[1,0]
	v_pk_mul_f32 v[104:105], v[104:105], v[202:203] op_sel_hi:[1,0]
	v_pk_mul_f32 v[102:103], v[102:103], v[202:203] op_sel_hi:[1,0]
	v_pk_mul_f32 v[100:101], v[100:101], v[202:203] op_sel_hi:[1,0]
	v_pk_mul_f32 v[98:99], v[98:99], v[202:203] op_sel_hi:[1,0]
	v_pk_mul_f32 v[96:97], v[96:97], v[202:203] op_sel_hi:[1,0]
	v_pk_mul_f32 v[94:95], v[94:95], v[202:203] op_sel_hi:[1,0]
	v_pk_mul_f32 v[92:93], v[92:93], v[202:203] op_sel_hi:[1,0]
	v_pk_mul_f32 v[90:91], v[90:91], v[202:203] op_sel_hi:[1,0]
	v_pk_mul_f32 v[88:89], v[88:89], v[202:203] op_sel_hi:[1,0]
	v_pk_mul_f32 v[86:87], v[86:87], v[202:203] op_sel_hi:[1,0]
	v_pk_mul_f32 v[84:85], v[84:85], v[202:203] op_sel_hi:[1,0]
	v_pk_mul_f32 v[82:83], v[82:83], v[202:203] op_sel_hi:[1,0]
	v_pk_mul_f32 v[80:81], v[80:81], v[202:203] op_sel_hi:[1,0]
	v_pk_mul_f32 v[30:31], v[30:31], v[202:203] op_sel_hi:[1,0]
	v_pk_mul_f32 v[28:29], v[28:29], v[202:203] op_sel_hi:[1,0]
	v_pk_mul_f32 v[26:27], v[26:27], v[202:203] op_sel_hi:[1,0]
	v_pk_mul_f32 v[24:25], v[24:25], v[202:203] op_sel_hi:[1,0]
	v_pk_mul_f32 v[22:23], v[22:23], v[202:203] op_sel_hi:[1,0]
	v_pk_mul_f32 v[20:21], v[20:21], v[202:203] op_sel_hi:[1,0]
	v_pk_mul_f32 v[18:19], v[18:19], v[202:203] op_sel_hi:[1,0]
	v_pk_mul_f32 v[16:17], v[16:17], v[202:203] op_sel_hi:[1,0]
.LBB0_1179:
	v_pk_fma_f32 v[128:129], v[128:129], s[58:59], v[200:201] op_sel_hi:[1,0,0] neg_lo:[0,0,1] neg_hi:[0,0,1]
	v_pk_fma_f32 v[144:145], v[144:145], s[58:59], v[200:201] op_sel_hi:[1,0,0] neg_lo:[0,0,1] neg_hi:[0,0,1]
	v_exp_f32_e32 v232, v128
	v_exp_f32_e32 v233, v129
	v_exp_f32_e32 v144, v144
	v_exp_f32_e32 v145, v145
	v_pk_fma_f32 v[128:129], v[130:131], s[58:59], v[200:201] op_sel_hi:[1,0,0] neg_lo:[0,0,1] neg_hi:[0,0,1]
	v_pk_fma_f32 v[130:131], v[146:147], s[58:59], v[200:201] op_sel_hi:[1,0,0] neg_lo:[0,0,1] neg_hi:[0,0,1]
	v_exp_f32_e32 v146, v128
	v_exp_f32_e32 v147, v129
	v_exp_f32_e32 v234, v130
	v_exp_f32_e32 v235, v131
	v_pk_fma_f32 v[132:133], v[132:133], s[58:59], v[200:201] op_sel_hi:[1,0,0] neg_lo:[0,0,1] neg_hi:[0,0,1]
	v_pk_fma_f32 v[148:149], v[148:149], s[58:59], v[200:201] op_sel_hi:[1,0,0] neg_lo:[0,0,1] neg_hi:[0,0,1]
	v_exp_f32_e32 v236, v132
	v_exp_f32_e32 v237, v133
	v_exp_f32_e32 v148, v148
	v_exp_f32_e32 v149, v149
	v_pk_fma_f32 v[132:133], v[134:135], s[58:59], v[200:201] op_sel_hi:[1,0,0] neg_lo:[0,0,1] neg_hi:[0,0,1]
	v_pk_fma_f32 v[134:135], v[150:151], s[58:59], v[200:201] op_sel_hi:[1,0,0] neg_lo:[0,0,1] neg_hi:[0,0,1]
	v_exp_f32_e32 v150, v132
	v_exp_f32_e32 v151, v133
	v_exp_f32_e32 v238, v134
	v_exp_f32_e32 v239, v135
	v_pk_fma_f32 v[132:133], v[136:137], s[58:59], v[200:201] op_sel_hi:[1,0,0] neg_lo:[0,0,1] neg_hi:[0,0,1]
	v_pk_fma_f32 v[134:135], v[152:153], s[58:59], v[200:201] op_sel_hi:[1,0,0] neg_lo:[0,0,1] neg_hi:[0,0,1]
	v_pk_add_f32 v[128:129], v[144:145], v[232:233]
	v_exp_f32_e32 v152, v132
	v_exp_f32_e32 v153, v133
	v_exp_f32_e32 v240, v134
	v_exp_f32_e32 v241, v135
	v_pk_fma_f32 v[132:133], v[138:139], s[58:59], v[200:201] op_sel_hi:[1,0,0] neg_lo:[0,0,1] neg_hi:[0,0,1]
	v_pk_fma_f32 v[134:135], v[154:155], s[58:59], v[200:201] op_sel_hi:[1,0,0] neg_lo:[0,0,1] neg_hi:[0,0,1]
	v_pk_add_f32 v[130:131], v[234:235], v[146:147]
	v_exp_f32_e32 v154, v132
	v_exp_f32_e32 v155, v133
	v_exp_f32_e32 v242, v134
	v_exp_f32_e32 v243, v135
	v_pk_fma_f32 v[132:133], v[140:141], s[58:59], v[200:201] op_sel_hi:[1,0,0] neg_lo:[0,0,1] neg_hi:[0,0,1]
	v_pk_fma_f32 v[134:135], v[156:157], s[58:59], v[200:201] op_sel_hi:[1,0,0] neg_lo:[0,0,1] neg_hi:[0,0,1]
	v_pk_add_f32 v[128:129], v[130:131], v[128:129]
	v_pk_add_f32 v[130:131], v[148:149], v[236:237]
	v_exp_f32_e32 v140, v132
	v_exp_f32_e32 v141, v133
	v_exp_f32_e32 v156, v134
	v_exp_f32_e32 v157, v135
	v_pk_fma_f32 v[132:133], v[142:143], s[58:59], v[200:201] op_sel_hi:[1,0,0] neg_lo:[0,0,1] neg_hi:[0,0,1]
	v_pk_fma_f32 v[134:135], v[158:159], s[58:59], v[200:201] op_sel_hi:[1,0,0] neg_lo:[0,0,1] neg_hi:[0,0,1]
	v_pk_add_f32 v[128:129], v[130:131], v[128:129]
	v_pk_add_f32 v[130:131], v[238:239], v[150:151]
	v_exp_f32_e32 v142, v132
	v_exp_f32_e32 v143, v133
	v_exp_f32_e32 v158, v134
	v_exp_f32_e32 v159, v135
	v_pk_add_f32 v[128:129], v[130:131], v[128:129]
	v_pk_add_f32 v[130:131], v[240:241], v[152:153]
	s_nop 0
	v_pk_add_f32 v[128:129], v[130:131], v[128:129]
	v_pk_add_f32 v[130:131], v[242:243], v[154:155]
	s_nop 0
	v_pk_add_f32 v[128:129], v[130:131], v[128:129]
	v_pk_add_f32 v[130:131], v[156:157], v[140:141]
	s_nop 0
	v_pk_add_f32 v[128:129], v[130:131], v[128:129]
	v_pk_add_f32 v[130:131], v[158:159], v[142:143]
	s_nop 0
	v_pk_add_f32 v[128:129], v[130:131], v[128:129]
	s_nop 0
	v_add_f32_e32 v230, v128, v129
	v_fmac_f32_e32 v230, v227, v202
	ds_read_b64_tr_b16 v[128:129], v225 offset:17408
	ds_read_b64_tr_b16 v[130:131], v225 offset:19968
	ds_read_b64_tr_b16 v[138:139], v225 offset:20032
	ds_read_b64_tr_b16 v[136:137], v225 offset:17472
	v_cvt_pk_bf16_f32 v132, v232, v233
	v_cvt_pk_bf16_f32 v133, v146, v147
	v_cvt_pk_bf16_f32 v134, v236, v237
	v_cvt_pk_bf16_f32 v135, v150, v151
	s_waitcnt lgkmcnt(2)
; template <int NS, int SI>
; __device__ __forceinline__ void attn_stream(const unsigned char* kbase, const unsigned char* vbase, const unsigned char* q_rd, bool mask_tail, int last_valid, int hh, float sc,
;                                             f32x16 (&O)[4], float& mrun, float& lrun) {
;     ...
;     __builtin_amdgcn_sched_barrier(0);
;     PV_GROUP(S0, 0, 0) PV_GROUP(S0, 0, 1) PV_GROUP(S1, 1, 0) PV_GROUP(S1, 1, 1)
	s_nop 0
	v_mfma_f32_32x32x16_bf16 v[112:127], v[128:131], v[132:135], v[112:127]
	s_waitcnt lgkmcnt(0)
	v_mfma_f32_32x32x16_bf16 v[96:111], v[136:139], v[132:135], v[96:111]
	ds_read_b64_tr_b16 v[128:129], v225 offset:17536
	ds_read_b64_tr_b16 v[130:131], v225 offset:20096
	ds_read_b64_tr_b16 v[138:139], v225 offset:20160
	ds_read_b64_tr_b16 v[136:137], v225 offset:17600
	s_waitcnt lgkmcnt(2)
	v_mfma_f32_32x32x16_bf16 v[80:95], v[128:131], v[132:135], v[80:95]
	s_waitcnt lgkmcnt(0)
	v_mfma_f32_32x32x16_bf16 v[16:31], v[136:139], v[132:135], v[16:31]
	ds_read_b64_tr_b16 v[128:129], v225 offset:22528
	ds_read_b64_tr_b16 v[130:131], v225 offset:25088
	ds_read_b64_tr_b16 v[138:139], v225 offset:25152
	ds_read_b64_tr_b16 v[136:137], v225 offset:22592
	v_cvt_pk_bf16_f32 v132, v152, v153
	v_cvt_pk_bf16_f32 v133, v154, v155
	v_cvt_pk_bf16_f32 v134, v140, v141
	v_cvt_pk_bf16_f32 v135, v142, v143
	s_waitcnt lgkmcnt(2)
	s_nop 0
	v_mfma_f32_32x32x16_bf16 v[112:127], v[128:131], v[132:135], v[112:127]
	s_waitcnt lgkmcnt(0)
	v_mfma_f32_32x32x16_bf16 v[96:111], v[136:139], v[132:135], v[96:111]
	ds_read_b64_tr_b16 v[128:129], v225 offset:22656
	ds_read_b64_tr_b16 v[130:131], v225 offset:25216
	ds_read_b64_tr_b16 v[138:139], v225 offset:25280
	ds_read_b64_tr_b16 v[136:137], v225 offset:22720
	s_waitcnt lgkmcnt(2)
	v_mfma_f32_32x32x16_bf16 v[80:95], v[128:131], v[132:135], v[80:95]
	s_waitcnt lgkmcnt(0)
	v_mfma_f32_32x32x16_bf16 v[16:31], v[136:139], v[132:135], v[16:31]
	ds_read_b64_tr_b16 v[128:129], v225 offset:27648
	ds_read_b64_tr_b16 v[130:131], v225 offset:30208
	ds_read_b64_tr_b16 v[138:139], v225 offset:30272
	ds_read_b64_tr_b16 v[136:137], v225 offset:27712
	v_cvt_pk_bf16_f32 v132, v144, v145
	v_cvt_pk_bf16_f32 v133, v234, v235
	v_cvt_pk_bf16_f32 v134, v148, v149
	v_cvt_pk_bf16_f32 v135, v238, v239
	s_waitcnt lgkmcnt(2)
	s_nop 0
	v_mfma_f32_32x32x16_bf16 v[112:127], v[128:131], v[132:135], v[112:127]
	s_waitcnt lgkmcnt(0)
	v_mfma_f32_32x32x16_bf16 v[96:111], v[136:139], v[132:135], v[96:111]
	ds_read_b64_tr_b16 v[128:129], v225 offset:27776
	ds_read_b64_tr_b16 v[130:131], v225 offset:30336
	ds_read_b64_tr_b16 v[138:139], v225 offset:30400
	ds_read_b64_tr_b16 v[136:137], v225 offset:27840
	s_waitcnt lgkmcnt(2)
	v_mfma_f32_32x32x16_bf16 v[80:95], v[128:131], v[132:135], v[80:95]
	s_waitcnt lgkmcnt(0)
	v_mfma_f32_32x32x16_bf16 v[16:31], v[136:139], v[132:135], v[16:31]
	ds_read_b64_tr_b16 v[128:129], v225 offset:32768
	ds_read_b64_tr_b16 v[130:131], v225 offset:35328
	ds_read_b64_tr_b16 v[138:139], v225 offset:35392
	ds_read_b64_tr_b16 v[136:137], v225 offset:32832
	v_cvt_pk_bf16_f32 v132, v240, v241
	v_cvt_pk_bf16_f32 v133, v242, v243
	v_cvt_pk_bf16_f32 v134, v156, v157
	v_cvt_pk_bf16_f32 v135, v158, v159
	s_waitcnt lgkmcnt(2)
	s_nop 0
	v_mfma_f32_32x32x16_bf16 v[112:127], v[128:131], v[132:135], v[112:127]
	s_waitcnt lgkmcnt(0)
	v_mfma_f32_32x32x16_bf16 v[96:111], v[136:139], v[132:135], v[96:111]
	ds_read_b64_tr_b16 v[128:129], v225 offset:32896
	ds_read_b64_tr_b16 v[130:131], v225 offset:35456
	ds_read_b64_tr_b16 v[138:139], v225 offset:35520
	ds_read_b64_tr_b16 v[136:137], v225 offset:32960
	s_waitcnt lgkmcnt(2)
	v_mfma_f32_32x32x16_bf16 v[80:95], v[128:131], v[132:135], v[80:95]
	s_waitcnt lgkmcnt(0)
	v_mfma_f32_32x32x16_bf16 v[16:31], v[136:139], v[132:135], v[16:31]
	v_mov_b32_e32 v229, v200
	v_mov_b32_e32 v227, v230
	s_or_b64 exec, exec, s[64:65]
	s_and_b64 vcc, exec, s[44:45]
	s_cbranch_vccz .LBB0_1171
	s_branch .LBB0_1172
